# grid barrier: the 3/4-th arriver of each XCD starts the early L2 write-back (instead of the first)
# baseline (speedup 1.0000x reference)
.LBB0_1934:
	s_or_b64 exec, exec, s[2:3]
	v_cvt_f32_u32_e32 v5, v3
	s_waitcnt vmcnt(0)
	v_readfirstlane_b32 s2, v4
	v_sub_u32_e32 v4, 0, v3
	v_rcp_iflag_f32_e32 v5, v5
	v_add_u32_e32 v6, s2, v0
	v_mul_f32_e32 v5, 0x4f7ffffe, v5
	v_cvt_u32_f32_e32 v5, v5
	v_mul_lo_u32 v0, v4, v5
	v_mul_hi_u32 v0, v5, v0
	v_add_u32_e32 v0, v5, v0
	v_mul_hi_u32 v0, v6, v0
	v_mul_lo_u32 v4, v0, v3
	v_sub_u32_e32 v4, v6, v4
	v_add_u32_e32 v5, 1, v0
	v_cmp_ge_u32_e32 vcc, v4, v3
	s_nop 1
	v_cndmask_b32_e32 v0, v0, v5, vcc
	v_sub_u32_e32 v5, v4, v3
	v_cndmask_b32_e32 v4, v4, v5, vcc
	v_add_u32_e32 v5, 1, v0
	v_cmp_ge_u32_e32 vcc, v4, v3
	v_add_u32_e32 v4, 1, v6
	s_nop 0
	v_cndmask_b32_e32 v0, v0, v5, vcc
	v_mul_lo_u32 v5, v3, v0
	v_sub_u32_e32 v7, v6, v5
	v_lshl_add_u32 v8, v3, 1, v3
	v_lshrrev_b32_e32 v8, 2, v8
	v_cmp_eq_u32_e32 vcc, v7, v8
	s_cbranch_vccz .Lef_skip
	buffer_wbl2 sc1
